# P4 compress stage 2: three rows per pass share each w2 column load, hid rows read by broadcast dwordx4 loads (f32 FMA chains in the original order)
# speedup vs baseline: 1.0083x; 1.0083x over previous
.LBB0_645:
	s_or_b64 exec, exec, s[0:1]
	v_mov_b32_e32 v7, 0
	s_waitcnt lgkmcnt(0)
	s_barrier
	v_mov_b32_e32 v0, s44
	v_mov_b32_e32 v1, s45
	v_mov_b32_e32 v6, 0x3308000
	global_load_dwordx2 v[4:5], v6, s[44:45] offset:72
	s_cmpk_gt_i32 s52, 0x2fcf
	v_lshrrev_b32_e32 v230, 5, v229
	s_waitcnt vmcnt(1)
	v_readfirstlane_b32 s4, v0
	v_readfirstlane_b32 s5, v1
	s_cbranch_scc1 .LBB0_661
	global_load_dwordx4 v[0:3], v6, s[44:45] offset:136
	global_load_dwordx2 v[12:13], v7, s[6:7]
	s_add_u32 s16, s4, 0x3f00000
	s_addc_u32 s21, s5, 0
	v_lshlrev_b32_e32 v6, 2, v229
	s_add_u32 s22, s4, 0x4600000
	v_lshlrev_b32_e32 v8, 9, v230
	v_lshlrev_b32_e32 v9, 3, v229
	s_movk_i32 s14, 0x3d07
	v_lshlrev_b32_e32 v10, 5, v229
	v_mbcnt_hi_u32_b32 v22, -1, v228
	s_addc_u32 s23, s5, 0
	s_mov_b64 s[2:3], 0x3400000
	v_or3_b32 v8, v8, v9, s14
	v_and_b32_e32 v23, 0x700, v10
	v_or_b32_e32 v10, 0x38f8, v10
	v_and_b32_e32 v9, 64, v22
	s_add_u32 s24, s4, 0x4500000
	v_cmp_lt_u32_e64 s[0:1], 31, v229
	s_mov_b64 s[6:7], 0x1000
	s_movk_i32 s17, 0x7fff
	v_mov_b32_e32 v20, 0x358637bd
	s_mov_b32 s20, 0xf800000
	v_mov_b32_e32 v21, 0x260
	s_mov_b64 s[8:9], 0x1f00
	v_xor_b32_e32 v24, 1, v22
	v_xor_b32_e32 v25, 2, v22
	v_lshlrev_b32_e32 v8, 1, v8
	v_lshlrev_b32_e32 v10, 1, v10
	v_add_u32_e32 v26, 64, v9
	s_addc_u32 s25, s5, 0
	s_mov_b32 s26, s52
	s_waitcnt vmcnt(1)
	v_lshl_add_u64 v[0:1], v[0:1], 0, v[6:7]
	s_waitcnt vmcnt(0)
	v_lshl_add_u64 v[12:13], v[12:13], 0, v[6:7]
	v_and_b32_e32 v6, 0xf8, v144
	v_lshl_add_u64 v[14:15], s[4:5], 0, v[6:7]
	v_lshl_add_u64 v[14:15], v[14:15], 0, s[2:3]
	s_mov_b32 s78, 0
	s_branch .LBB0_648
.LBB0_647:
	s_cmp_eq_u32 s78, 0
	s_cbranch_scc1 .Lc3_none
	s_add_i32 s26, s26, s54
	s_sub_i32 s14, s26, s79
	v_mov_b32_e32 v18, 0
	v_mov_b32_e32 v19, 0
	v_mov_b32_e32 v9, 0
	s_cmp_eq_u32 s78, 2
	s_cbranch_scc0 .Lc3_r2
	v_mov_b32_e32 v6, v168
	s_mov_b32 s78, 1
	s_branch .Lc3_epi
.Lc3_r2:
	v_mov_b32_e32 v6, v169
	s_mov_b32 s78, 0
	s_branch .Lc3_epi

.LBB0_648:
	s_mul_hi_i32 s2, s26, 0x2ad5802b
	s_lshr_b32 s3, s2, 31
	s_ashr_i32 s2, s2, 10
	s_add_i32 s28, s2, s3
	v_lshl_or_b32 v16, s28, 6, v229
	v_ashrrev_i32_e32 v17, 31, v16
	v_lshl_add_u64 v[16:17], v[16:17], 2, v[2:3]
	global_load_dword v6, v[16:17], off
	s_mul_i32 s2, s28, 0x17e8
	s_sub_i32 s14, s26, s2
	s_ashr_i32 s29, s28, 31
	s_mul_i32 s2, s28, 0x1800
	s_ashr_i32 s15, s14, 31
	s_mul_hi_i32 s3, s28, 0x1800
	s_add_u32 s2, s2, s14
	s_addc_u32 s3, s3, s15
	s_lshl_b64 s[2:3], s[2:3], 9
	s_add_u32 s2, s16, s2
	s_addc_u32 s3, s21, s3
	s_lshl_b64 s[28:29], s[28:29], 16
	v_mov_b32_e32 v9, 0
	v_lshl_add_u64 v[16:17], v[0:1], 0, s[28:29]
	s_mov_b32 s15, -2
	v_mov_b32_e32 v18, 0
	v_mov_b32_e32 v19, v9
	s_lshl_b32 s80, s54, 1
	s_add_i32 s80, s80, s26
	s_cmp_lt_i32 s80, 0x2fd0
	s_cbranch_scc0 .Lc3_single
	s_cmp_ge_i32 s26, 0x17e8
	s_cselect_b32 s81, 1, 0
	s_cmp_ge_i32 s80, 0x17e8
	s_cselect_b32 s80, 1, 0
	s_cmp_lg_u32 s80, s81
	s_cbranch_scc1 .Lc3_single
	s_sub_i32 s79, s26, s14
	s_lshl_b32 s80, s54, 9
	s_mov_b64 s[60:61], s[2:3]
	s_add_u32 s64, s2, s80
	s_addc_u32 s65, s3, 0
	s_add_u32 s72, s64, s80
	s_addc_u32 s73, s65, 0
	s_mov_b64 s[82:83], 0x1000
	v_mov_b32_e32 v167, 0
	v_mov_b32_e32 v178, v16
	v_mov_b32_e32 v179, v17
	global_load_dwordx4 v[72:75], v167, s[60:61]
	global_load_dwordx4 v[76:79], v167, s[64:65]
	global_load_dwordx4 v[80:83], v167, s[72:73]
	global_load_dword v96, v[178:179], off
	global_load_dword v97, v[178:179], off offset:256
	global_load_dword v98, v[178:179], off offset:512
	global_load_dword v99, v[178:179], off offset:768
	global_load_dword v100, v[178:179], off offset:1024
	global_load_dword v101, v[178:179], off offset:1280
	global_load_dword v102, v[178:179], off offset:1536
	global_load_dword v103, v[178:179], off offset:1792
	v_mov_b32_e32 v61, 0
	v_mov_b32_e32 v62, 0
	v_mov_b32_e32 v63, 0
	v_mov_b32_e32 v65, 0
	v_mov_b32_e32 v66, 0
	v_mov_b32_e32 v67, 0
	v_mov_b32_e32 v69, 0
	v_mov_b32_e32 v70, 0
	v_mov_b32_e32 v71, 0
	s_mov_b32 s77, 0
	s_waitcnt vmcnt(11)
	v_mov_b32_e32 v60, v6
	v_mov_b32_e32 v64, v6
	v_mov_b32_e32 v68, v6
.Lc3_loop:
	global_load_dwordx4 v[84:87], v167, s[60:61] offset:16
	global_load_dwordx4 v[88:91], v167, s[64:65] offset:16
	global_load_dwordx4 v[92:95], v167, s[72:73] offset:16
	global_load_dword v104, v[178:179], off offset:2048
	global_load_dword v105, v[178:179], off offset:2304
	global_load_dword v106, v[178:179], off offset:2560
	global_load_dword v107, v[178:179], off offset:2816
	global_load_dword v108, v[178:179], off offset:3072
	global_load_dword v109, v[178:179], off offset:3328
	global_load_dword v110, v[178:179], off offset:3584
	global_load_dword v111, v[178:179], off offset:3840
	s_waitcnt vmcnt(11)
	v_lshlrev_b32_e32 v165, 16, v72
	v_and_b32_e32 v166, 0xffff0000, v72
	v_fmac_f32_e32 v60, v165, v96
	v_fmac_f32_e32 v61, v166, v97
	v_lshlrev_b32_e32 v59, 16, v76
	v_and_b32_e32 v177, 0xffff0000, v76
	v_fmac_f32_e32 v64, v59, v96
	v_fmac_f32_e32 v65, v177, v97
	v_lshlrev_b32_e32 v165, 16, v80
	v_and_b32_e32 v166, 0xffff0000, v80
	v_fmac_f32_e32 v68, v165, v96
	v_fmac_f32_e32 v69, v166, v97
	v_lshlrev_b32_e32 v165, 16, v73
	v_and_b32_e32 v166, 0xffff0000, v73
	v_fmac_f32_e32 v62, v165, v98
	v_fmac_f32_e32 v63, v166, v99
	v_lshlrev_b32_e32 v59, 16, v77
	v_and_b32_e32 v177, 0xffff0000, v77
	v_fmac_f32_e32 v66, v59, v98
	v_fmac_f32_e32 v67, v177, v99
	v_lshlrev_b32_e32 v165, 16, v81
	v_and_b32_e32 v166, 0xffff0000, v81
	v_fmac_f32_e32 v70, v165, v98
	v_fmac_f32_e32 v71, v166, v99
	v_lshlrev_b32_e32 v165, 16, v74
	v_and_b32_e32 v166, 0xffff0000, v74
	v_fmac_f32_e32 v60, v165, v100
	v_fmac_f32_e32 v61, v166, v101
	v_lshlrev_b32_e32 v59, 16, v78
	v_and_b32_e32 v177, 0xffff0000, v78
	v_fmac_f32_e32 v64, v59, v100
	v_fmac_f32_e32 v65, v177, v101
	v_lshlrev_b32_e32 v165, 16, v82
	v_and_b32_e32 v166, 0xffff0000, v82
	v_fmac_f32_e32 v68, v165, v100
	v_fmac_f32_e32 v69, v166, v101
	v_lshlrev_b32_e32 v165, 16, v75
	v_and_b32_e32 v166, 0xffff0000, v75
	v_fmac_f32_e32 v62, v165, v102
	v_fmac_f32_e32 v63, v166, v103
	v_lshlrev_b32_e32 v59, 16, v79
	v_and_b32_e32 v177, 0xffff0000, v79
	v_fmac_f32_e32 v66, v59, v102
	v_fmac_f32_e32 v67, v177, v103
	v_lshlrev_b32_e32 v165, 16, v83
	v_and_b32_e32 v166, 0xffff0000, v83
	v_fmac_f32_e32 v70, v165, v102
	v_fmac_f32_e32 v71, v166, v103
	s_add_u32 s60, s60, 32
	s_addc_u32 s61, s61, 0
	s_add_u32 s64, s64, 32
	s_addc_u32 s65, s65, 0
	s_add_u32 s72, s72, 32
	s_addc_u32 s73, s73, 0
	v_lshl_add_u64 v[178:179], v[178:179], 0, s[82:83]
	s_cmp_eq_u32 s77, 15
	s_cbranch_scc1 .Lc3_last
	global_load_dwordx4 v[72:75], v167, s[60:61]
	global_load_dwordx4 v[76:79], v167, s[64:65]
	global_load_dwordx4 v[80:83], v167, s[72:73]
	global_load_dword v96, v[178:179], off
	global_load_dword v97, v[178:179], off offset:256
	global_load_dword v98, v[178:179], off offset:512
	global_load_dword v99, v[178:179], off offset:768
	global_load_dword v100, v[178:179], off offset:1024
	global_load_dword v101, v[178:179], off offset:1280
	global_load_dword v102, v[178:179], off offset:1536
	global_load_dword v103, v[178:179], off offset:1792
	s_waitcnt vmcnt(11)
	v_lshlrev_b32_e32 v165, 16, v84
	v_and_b32_e32 v166, 0xffff0000, v84
	v_fmac_f32_e32 v60, v165, v104
	v_fmac_f32_e32 v61, v166, v105
	v_lshlrev_b32_e32 v59, 16, v88
	v_and_b32_e32 v177, 0xffff0000, v88
	v_fmac_f32_e32 v64, v59, v104
	v_fmac_f32_e32 v65, v177, v105
	v_lshlrev_b32_e32 v165, 16, v92
	v_and_b32_e32 v166, 0xffff0000, v92
	v_fmac_f32_e32 v68, v165, v104
	v_fmac_f32_e32 v69, v166, v105
	v_lshlrev_b32_e32 v165, 16, v85
	v_and_b32_e32 v166, 0xffff0000, v85
	v_fmac_f32_e32 v62, v165, v106
	v_fmac_f32_e32 v63, v166, v107
	v_lshlrev_b32_e32 v59, 16, v89
	v_and_b32_e32 v177, 0xffff0000, v89
	v_fmac_f32_e32 v66, v59, v106
	v_fmac_f32_e32 v67, v177, v107
	v_lshlrev_b32_e32 v165, 16, v93
	v_and_b32_e32 v166, 0xffff0000, v93
	v_fmac_f32_e32 v70, v165, v106
	v_fmac_f32_e32 v71, v166, v107
	v_lshlrev_b32_e32 v165, 16, v86
	v_and_b32_e32 v166, 0xffff0000, v86
	v_fmac_f32_e32 v60, v165, v108
	v_fmac_f32_e32 v61, v166, v109
	v_lshlrev_b32_e32 v59, 16, v90
	v_and_b32_e32 v177, 0xffff0000, v90
	v_fmac_f32_e32 v64, v59, v108
	v_fmac_f32_e32 v65, v177, v109
	v_lshlrev_b32_e32 v165, 16, v94
	v_and_b32_e32 v166, 0xffff0000, v94
	v_fmac_f32_e32 v68, v165, v108
	v_fmac_f32_e32 v69, v166, v109
	v_lshlrev_b32_e32 v165, 16, v87
	v_and_b32_e32 v166, 0xffff0000, v87
	v_fmac_f32_e32 v62, v165, v110
	v_fmac_f32_e32 v63, v166, v111
	v_lshlrev_b32_e32 v59, 16, v91
	v_and_b32_e32 v177, 0xffff0000, v91
	v_fmac_f32_e32 v66, v59, v110
	v_fmac_f32_e32 v67, v177, v111
	v_lshlrev_b32_e32 v165, 16, v95
	v_and_b32_e32 v166, 0xffff0000, v95
	v_fmac_f32_e32 v70, v165, v110
	v_fmac_f32_e32 v71, v166, v111
	s_add_u32 s77, s77, 1
	s_branch .Lc3_loop
.Lc3_last:
	s_waitcnt vmcnt(0)
	v_lshlrev_b32_e32 v165, 16, v84
	v_and_b32_e32 v166, 0xffff0000, v84
	v_fmac_f32_e32 v60, v165, v104
	v_fmac_f32_e32 v61, v166, v105
	v_lshlrev_b32_e32 v59, 16, v88
	v_and_b32_e32 v177, 0xffff0000, v88
	v_fmac_f32_e32 v64, v59, v104
	v_fmac_f32_e32 v65, v177, v105
	v_lshlrev_b32_e32 v165, 16, v92
	v_and_b32_e32 v166, 0xffff0000, v92
	v_fmac_f32_e32 v68, v165, v104
	v_fmac_f32_e32 v69, v166, v105
	v_lshlrev_b32_e32 v165, 16, v85
	v_and_b32_e32 v166, 0xffff0000, v85
	v_fmac_f32_e32 v62, v165, v106
	v_fmac_f32_e32 v63, v166, v107
	v_lshlrev_b32_e32 v59, 16, v89
	v_and_b32_e32 v177, 0xffff0000, v89
	v_fmac_f32_e32 v66, v59, v106
	v_fmac_f32_e32 v67, v177, v107
	v_lshlrev_b32_e32 v165, 16, v93
	v_and_b32_e32 v166, 0xffff0000, v93
	v_fmac_f32_e32 v70, v165, v106
	v_fmac_f32_e32 v71, v166, v107
	v_lshlrev_b32_e32 v165, 16, v86
	v_and_b32_e32 v166, 0xffff0000, v86
	v_fmac_f32_e32 v60, v165, v108
	v_fmac_f32_e32 v61, v166, v109
	v_lshlrev_b32_e32 v59, 16, v90
	v_and_b32_e32 v177, 0xffff0000, v90
	v_fmac_f32_e32 v64, v59, v108
	v_fmac_f32_e32 v65, v177, v109
	v_lshlrev_b32_e32 v165, 16, v94
	v_and_b32_e32 v166, 0xffff0000, v94
	v_fmac_f32_e32 v68, v165, v108
	v_fmac_f32_e32 v69, v166, v109
	v_lshlrev_b32_e32 v165, 16, v87
	v_and_b32_e32 v166, 0xffff0000, v87
	v_fmac_f32_e32 v62, v165, v110
	v_fmac_f32_e32 v63, v166, v111
	v_lshlrev_b32_e32 v59, 16, v91
	v_and_b32_e32 v177, 0xffff0000, v91
	v_fmac_f32_e32 v66, v59, v110
	v_fmac_f32_e32 v67, v177, v111
	v_lshlrev_b32_e32 v165, 16, v95
	v_and_b32_e32 v166, 0xffff0000, v95
	v_fmac_f32_e32 v70, v165, v110
	v_fmac_f32_e32 v71, v166, v111
	v_add_f32_e32 v60, v60, v61
	v_add_f32_e32 v62, v62, v63
	v_add_f32_e32 v6, v60, v62
	v_add_f32_e32 v64, v64, v65
	v_add_f32_e32 v66, v66, v67
	v_add_f32_e32 v168, v64, v66
	v_add_f32_e32 v68, v68, v69
	v_add_f32_e32 v70, v70, v71
	v_add_f32_e32 v169, v68, v70
	v_mov_b32_e32 v18, 0
	v_mov_b32_e32 v19, 0
	v_mov_b32_e32 v9, 0
	s_mov_b32 s78, 2
	s_branch .Lc3_epi
.Lc3_single:
	v_mov_b64_e32 v[36:37], s[2:3]
	global_load_dword v11, v[16:17], off
	global_load_dword v38, v[16:17], off offset:256
	global_load_dword v39, v[16:17], off offset:512
	global_load_dword v27, v[16:17], off offset:768
	global_load_dword v46, v[16:17], off offset:1024
	global_load_dword v40, v[16:17], off offset:1280
	global_load_dword v41, v[16:17], off offset:1536
	global_load_dword v47, v[16:17], off offset:1792
	global_load_dword v48, v[16:17], off offset:2048
	global_load_dword v42, v[16:17], off offset:2304
	global_load_dword v43, v[16:17], off offset:2560
	global_load_dword v49, v[16:17], off offset:2816
	global_load_dword v50, v[16:17], off offset:3072
	global_load_dword v44, v[16:17], off offset:3328
	global_load_dwordx4 v[28:31], v[36:37], off
	global_load_dwordx4 v[32:35], v[36:37], off offset:16
	global_load_dword v45, v[16:17], off offset:3584
	global_load_dword v51, v[16:17], off offset:3840
	s_add_u32 s2, s2, 32
	s_addc_u32 s3, s3, 0
	v_lshl_add_u64 v[16:17], v[16:17], 0, s[6:7]
	s_mov_b32 s15, 7

.Lc3_epi:
	s_mul_i32 s2, s14, 0xffff8081
	s_lshr_b32 s2, s2, 16
	s_add_i32 s2, s2, s14
	s_sext_i32_i16 s3, s2
	s_ashr_i32 s3, s3, 7
	s_bfe_u32 s2, s2, 0x1000f
	s_add_i32 s15, s3, s2
	s_mul_i32 s2, s15, 0xff
	s_sub_i32 s2, s14, s2
	v_add_f32_e32 v6, v6, v18
	v_add_f32_e32 v9, v19, v9
	s_add_i32 s14, s26, 0x17e7
	s_sext_i32_i16 s27, s2
	v_add_f32_e32 v11, v6, v9
	s_mov_b64 s[2:3], -1
	s_cmpk_gt_u32 s14, 0x2fce
	s_sext_i32_i16 s14, s15
	s_cbranch_scc0 .LBB0_654
	s_ashr_i32 s15, s14, 31
	s_lshl_b64 s[2:3], s[14:15], 15
	s_add_u32 s2, s22, s2
	s_addc_u32 s3, s23, s3
	s_lshr_b32 s15, s27, 1
	s_and_b32 s15, s15, 4
	s_and_b32 s28, s27, 3
	v_bfe_u32 v6, v11, 16, 1
	s_or_b32 s15, s28, s15
	s_ashr_i32 s28, s27, 5
	s_lshr_b32 s30, s27, 3
	v_add3_u32 v9, v11, v6, s17
	s_ashr_i32 s29, s28, 31
	v_and_or_b32 v6, s30, 2, v230
	s_lshl_b32 s30, s27, 3
	s_and_b32 s30, s30, 32
	s_lshl_b64 s[28:29], s[28:29], 12
	v_lshlrev_b32_e32 v6, 6, v6
	s_add_u32 s28, s2, s28
	v_or3_b32 v6, v6, s30, v172
	s_addc_u32 s29, s3, s29
	s_lshl_b32 s15, s15, 1
	v_lshl_or_b32 v6, v6, 4, s15
	s_and_b32 s15, s27, 0xffff
	v_lshl_add_u64 v[16:17], s[28:29], 0, v[6:7]
	s_cmpk_lg_i32 s15, 0xfe
	flat_store_short_d16_hi v[16:17], v9
	s_cbranch_scc1 .LBB0_653
	v_mov_b32_e32 v9, v7
	v_lshl_add_u64 v[16:17], s[2:3], 0, v[8:9]
	flat_store_short v[16:17], v7
